# GLA second pass: the per-step LDS element reads issued in batches ahead of the exp/scale/write-back chain
# speedup vs baseline: 1.0110x; 1.0031x over previous
; DEVI float bf2f(u16 b) { return __uint_as_float(((unsigned)b) << 16); }
; DEVI u16 f2bf(float f) { return (u16)(cvt_pk(f, 0.f) & 0xffffu); }
; template <int KIND>
; DEVI void mix_state_phase(unsigned char* smem, const MixArgs a) {
;     ...
;             for (int t = sg * 32; t < sg * 32 + 32; ++t) { Bc += gla_la(gl, t, w2r, gb);
;                 const float kv = bf2f(KT[t * LP + ch]); KT[t * LP + ch] = f2bf(kv * __expf(tot - Bc)); }
;             if (sg == 0) a.dec[(size_t)item * 128 + ch] = __expf(tot);
.LBB0_516:
	v_add_u32_e32 v145, 0xfffffef0, v124
	ds_read_u16 v129, v145
	ds_read_u16 v130, v145 offset:272
	ds_read_u16 v131, v145 offset:544
	ds_read_u16 v132, v145 offset:816
	ds_read_u16 v133, v145 offset:1088
	ds_read_u16 v134, v145 offset:1360
	ds_read_u16 v135, v145 offset:1632
	ds_read_u16 v136, v145 offset:1904
	ds_read_u16 v137, v145 offset:2176
	ds_read_u16 v138, v145 offset:2448
	ds_read_u16 v139, v145 offset:2720
	ds_read_u16 v140, v145 offset:2992
	s_waitcnt lgkmcnt(11)
	ds_read_u16 v141, v145 offset:3264
	s_waitcnt lgkmcnt(11)
	ds_read_u16 v142, v145 offset:3536
	s_waitcnt lgkmcnt(11)
	ds_read_u16 v143, v145 offset:3808
	s_waitcnt lgkmcnt(11)
	ds_read_u16 v144, v145 offset:4080
	s_waitcnt lgkmcnt(0)
	v_fmac_f32_e32 v123, 0x3d800000, v192
	v_add_u32_e32 v126, 0xfffffef0, v124
	v_sub_f32_e32 v128, v122, v123
	v_mul_f32_e32 v128, 0x3fb8aa3b, v128
	v_exp_f32_e32 v128, v128
	v_lshlrev_b32_e32 v127, 16, v129
	v_mul_f32_e32 v127, v128, v127
	v_cvt_pk_bf16_f32 v127, v127, s0
	ds_write_b16 v126, v127
	v_fmac_f32_e32 v123, 0x3d800000, v193
	v_sub_f32_e32 v126, v122, v123
	v_mul_f32_e32 v126, 0x3fb8aa3b, v126
	v_exp_f32_e32 v126, v126
	v_lshlrev_b32_e32 v125, 16, v130
	v_mul_f32_e32 v125, v126, v125
	v_cvt_pk_bf16_f32 v125, v125, s0
	s_addk_i32 s0, 0x80
	ds_write_b16 v124, v125
	v_add_u32_e32 v124, 0x220, v124
	v_fmac_f32_e32 v123, 0x3d800000, v194
	v_add_u32_e32 v126, 0xfffffef0, v124
	v_sub_f32_e32 v128, v122, v123
	v_mul_f32_e32 v128, 0x3fb8aa3b, v128
	v_exp_f32_e32 v128, v128
	v_lshlrev_b32_e32 v127, 16, v131
	v_mul_f32_e32 v127, v128, v127
	v_cvt_pk_bf16_f32 v127, v127, s0
	ds_write_b16 v126, v127
	v_fmac_f32_e32 v123, 0x3d800000, v195
	v_sub_f32_e32 v126, v122, v123
	v_mul_f32_e32 v126, 0x3fb8aa3b, v126
	v_exp_f32_e32 v126, v126
	v_lshlrev_b32_e32 v125, 16, v132
	v_mul_f32_e32 v125, v126, v125
	v_cvt_pk_bf16_f32 v125, v125, s0
	s_addk_i32 s0, 0x80
	ds_write_b16 v124, v125
	v_add_u32_e32 v124, 0x220, v124
	v_fmac_f32_e32 v123, 0x3d800000, v196
	v_add_u32_e32 v126, 0xfffffef0, v124
	v_sub_f32_e32 v128, v122, v123
	v_mul_f32_e32 v128, 0x3fb8aa3b, v128
	v_exp_f32_e32 v128, v128
	v_lshlrev_b32_e32 v127, 16, v133
	v_mul_f32_e32 v127, v128, v127
	v_cvt_pk_bf16_f32 v127, v127, s0
	ds_write_b16 v126, v127
	v_fmac_f32_e32 v123, 0x3d800000, v197
	v_sub_f32_e32 v126, v122, v123
	v_mul_f32_e32 v126, 0x3fb8aa3b, v126
	v_exp_f32_e32 v126, v126
	v_lshlrev_b32_e32 v125, 16, v134
	v_mul_f32_e32 v125, v126, v125
	v_cvt_pk_bf16_f32 v125, v125, s0
	s_addk_i32 s0, 0x80
	ds_write_b16 v124, v125
	v_add_u32_e32 v124, 0x220, v124
	v_fmac_f32_e32 v123, 0x3d800000, v198
	v_add_u32_e32 v126, 0xfffffef0, v124
	v_sub_f32_e32 v128, v122, v123
	v_mul_f32_e32 v128, 0x3fb8aa3b, v128
	v_exp_f32_e32 v128, v128
	v_lshlrev_b32_e32 v127, 16, v135
	v_mul_f32_e32 v127, v128, v127
	v_cvt_pk_bf16_f32 v127, v127, s0
	ds_write_b16 v126, v127
	v_fmac_f32_e32 v123, 0x3d800000, v199
	v_sub_f32_e32 v126, v122, v123
	v_mul_f32_e32 v126, 0x3fb8aa3b, v126
	v_exp_f32_e32 v126, v126
	v_lshlrev_b32_e32 v125, 16, v136
	v_mul_f32_e32 v125, v126, v125
	v_cvt_pk_bf16_f32 v125, v125, s0
	s_addk_i32 s0, 0x80
	ds_write_b16 v124, v125
	v_add_u32_e32 v124, 0x220, v124
	v_fmac_f32_e32 v123, 0x3d800000, v200
	v_add_u32_e32 v126, 0xfffffef0, v124
	v_sub_f32_e32 v128, v122, v123
	v_mul_f32_e32 v128, 0x3fb8aa3b, v128
	v_exp_f32_e32 v128, v128
	v_lshlrev_b32_e32 v127, 16, v137
	v_mul_f32_e32 v127, v128, v127
	v_cvt_pk_bf16_f32 v127, v127, s0
	ds_write_b16 v126, v127
	v_fmac_f32_e32 v123, 0x3d800000, v201
	v_sub_f32_e32 v126, v122, v123
	v_mul_f32_e32 v126, 0x3fb8aa3b, v126
	v_exp_f32_e32 v126, v126
	v_lshlrev_b32_e32 v125, 16, v138
	v_mul_f32_e32 v125, v126, v125
	v_cvt_pk_bf16_f32 v125, v125, s0
	s_addk_i32 s0, 0x80
	ds_write_b16 v124, v125
	v_add_u32_e32 v124, 0x220, v124
	v_fmac_f32_e32 v123, 0x3d800000, v202
	v_add_u32_e32 v126, 0xfffffef0, v124
	v_sub_f32_e32 v128, v122, v123
	v_mul_f32_e32 v128, 0x3fb8aa3b, v128
	v_exp_f32_e32 v128, v128
	v_lshlrev_b32_e32 v127, 16, v139
	v_mul_f32_e32 v127, v128, v127
	v_cvt_pk_bf16_f32 v127, v127, s0
	ds_write_b16 v126, v127
	v_fmac_f32_e32 v123, 0x3d800000, v203
	v_sub_f32_e32 v126, v122, v123
	v_mul_f32_e32 v126, 0x3fb8aa3b, v126
	v_exp_f32_e32 v126, v126
	v_lshlrev_b32_e32 v125, 16, v140
	v_mul_f32_e32 v125, v126, v125
	v_cvt_pk_bf16_f32 v125, v125, s0
	s_addk_i32 s0, 0x80
	ds_write_b16 v124, v125
	v_add_u32_e32 v124, 0x220, v124
	v_fmac_f32_e32 v123, 0x3d800000, v204
	v_add_u32_e32 v126, 0xfffffef0, v124
	v_sub_f32_e32 v128, v122, v123
	v_mul_f32_e32 v128, 0x3fb8aa3b, v128
	v_exp_f32_e32 v128, v128
	v_lshlrev_b32_e32 v127, 16, v141
	v_mul_f32_e32 v127, v128, v127
	v_cvt_pk_bf16_f32 v127, v127, s0
	ds_write_b16 v126, v127
	v_fmac_f32_e32 v123, 0x3d800000, v205
	v_sub_f32_e32 v126, v122, v123
	v_mul_f32_e32 v126, 0x3fb8aa3b, v126
	v_exp_f32_e32 v126, v126
	v_lshlrev_b32_e32 v125, 16, v142
	v_mul_f32_e32 v125, v126, v125
	v_cvt_pk_bf16_f32 v125, v125, s0
	s_addk_i32 s0, 0x80
	ds_write_b16 v124, v125
	v_add_u32_e32 v124, 0x220, v124
	v_fmac_f32_e32 v123, 0x3d800000, v206
	v_add_u32_e32 v126, 0xfffffef0, v124
	v_sub_f32_e32 v128, v122, v123
	v_mul_f32_e32 v128, 0x3fb8aa3b, v128
	v_exp_f32_e32 v128, v128
	v_lshlrev_b32_e32 v127, 16, v143
	v_mul_f32_e32 v127, v128, v127
	v_cvt_pk_bf16_f32 v127, v127, s0
	ds_write_b16 v126, v127
	v_fmac_f32_e32 v123, 0x3d800000, v207
	v_sub_f32_e32 v126, v122, v123
	v_mul_f32_e32 v126, 0x3fb8aa3b, v126
	v_exp_f32_e32 v126, v126
	v_lshlrev_b32_e32 v125, 16, v144
	v_mul_f32_e32 v125, v126, v125
	v_cvt_pk_bf16_f32 v125, v125, s0
	s_addk_i32 s0, 0x80
	ds_write_b16 v124, v125
	v_add_u32_e32 v124, 0x220, v124
	v_add_u32_e32 v145, 0xfffffef0, v124
	ds_read_u16 v129, v145
	ds_read_u16 v130, v145 offset:272
	ds_read_u16 v131, v145 offset:544
	ds_read_u16 v132, v145 offset:816
	ds_read_u16 v133, v145 offset:1088
	ds_read_u16 v134, v145 offset:1360
	ds_read_u16 v135, v145 offset:1632
	ds_read_u16 v136, v145 offset:1904
	ds_read_u16 v137, v145 offset:2176
	ds_read_u16 v138, v145 offset:2448
	ds_read_u16 v139, v145 offset:2720
	ds_read_u16 v140, v145 offset:2992
	s_waitcnt lgkmcnt(11)
; DEVI float bf2f(u16 b) { return __uint_as_float(((unsigned)b) << 16); }
; DEVI u16 f2bf(float f) { return (u16)(cvt_pk(f, 0.f) & 0xffffu); }
; template <int KIND>
; DEVI void mix_state_phase(unsigned char* smem, const MixArgs a) {
;     ...
;             for (int t = sg * 32; t < sg * 32 + 32; ++t) { Bc += gla_la(gl, t, w2r, gb);
;                 const float kv = bf2f(KT[t * LP + ch]); KT[t * LP + ch] = f2bf(kv * __expf(tot - Bc)); }
;             if (sg == 0) a.dec[(size_t)item * 128 + ch] = __expf(tot);
	ds_read_u16 v141, v145 offset:3264
	s_waitcnt lgkmcnt(11)
	ds_read_u16 v142, v145 offset:3536
	s_waitcnt lgkmcnt(11)
	ds_read_u16 v143, v145 offset:3808
	s_waitcnt lgkmcnt(11)
	ds_read_u16 v144, v145 offset:4080
	s_waitcnt lgkmcnt(0)
	v_fmac_f32_e32 v123, 0x3d800000, v213
	v_add_u32_e32 v126, 0xfffffef0, v124
	v_sub_f32_e32 v128, v122, v123
	v_mul_f32_e32 v128, 0x3fb8aa3b, v128
	v_exp_f32_e32 v128, v128
	v_lshlrev_b32_e32 v127, 16, v129
	v_mul_f32_e32 v127, v128, v127
	v_cvt_pk_bf16_f32 v127, v127, s0
	ds_write_b16 v126, v127
	v_fmac_f32_e32 v123, 0x3d800000, v214
	v_sub_f32_e32 v126, v122, v123
	v_mul_f32_e32 v126, 0x3fb8aa3b, v126
	v_exp_f32_e32 v126, v126
	v_lshlrev_b32_e32 v125, 16, v130
	v_mul_f32_e32 v125, v126, v125
	v_cvt_pk_bf16_f32 v125, v125, s0
	s_addk_i32 s0, 0x80
	ds_write_b16 v124, v125
	v_add_u32_e32 v124, 0x220, v124
	v_fmac_f32_e32 v123, 0x3d800000, v215
	v_add_u32_e32 v126, 0xfffffef0, v124
	v_sub_f32_e32 v128, v122, v123
	v_mul_f32_e32 v128, 0x3fb8aa3b, v128
	v_exp_f32_e32 v128, v128
	v_lshlrev_b32_e32 v127, 16, v131
	v_mul_f32_e32 v127, v128, v127
	v_cvt_pk_bf16_f32 v127, v127, s0
	ds_write_b16 v126, v127
	v_fmac_f32_e32 v123, 0x3d800000, v216
	v_sub_f32_e32 v126, v122, v123
	v_mul_f32_e32 v126, 0x3fb8aa3b, v126
	v_exp_f32_e32 v126, v126
	v_lshlrev_b32_e32 v125, 16, v132
	v_mul_f32_e32 v125, v126, v125
	v_cvt_pk_bf16_f32 v125, v125, s0
	s_addk_i32 s0, 0x80
	ds_write_b16 v124, v125
	v_add_u32_e32 v124, 0x220, v124
	v_fmac_f32_e32 v123, 0x3d800000, v217
	v_add_u32_e32 v126, 0xfffffef0, v124
	v_sub_f32_e32 v128, v122, v123
	v_mul_f32_e32 v128, 0x3fb8aa3b, v128
	v_exp_f32_e32 v128, v128
	v_lshlrev_b32_e32 v127, 16, v133
	v_mul_f32_e32 v127, v128, v127
	v_cvt_pk_bf16_f32 v127, v127, s0
	ds_write_b16 v126, v127
	v_fmac_f32_e32 v123, 0x3d800000, v218
	v_sub_f32_e32 v126, v122, v123
	v_mul_f32_e32 v126, 0x3fb8aa3b, v126
	v_exp_f32_e32 v126, v126
	v_lshlrev_b32_e32 v125, 16, v134
	v_mul_f32_e32 v125, v126, v125
	v_cvt_pk_bf16_f32 v125, v125, s0
	s_addk_i32 s0, 0x80
	ds_write_b16 v124, v125
	v_add_u32_e32 v124, 0x220, v124
	v_fmac_f32_e32 v123, 0x3d800000, v219
	v_add_u32_e32 v126, 0xfffffef0, v124
	v_sub_f32_e32 v128, v122, v123
	v_mul_f32_e32 v128, 0x3fb8aa3b, v128
	v_exp_f32_e32 v128, v128
	v_lshlrev_b32_e32 v127, 16, v135
	v_mul_f32_e32 v127, v128, v127
	v_cvt_pk_bf16_f32 v127, v127, s0
	ds_write_b16 v126, v127
	v_fmac_f32_e32 v123, 0x3d800000, v220
	v_sub_f32_e32 v126, v122, v123
	v_mul_f32_e32 v126, 0x3fb8aa3b, v126
	v_exp_f32_e32 v126, v126
	v_lshlrev_b32_e32 v125, 16, v136
	v_mul_f32_e32 v125, v126, v125
	v_cvt_pk_bf16_f32 v125, v125, s0
	s_addk_i32 s0, 0x80
	ds_write_b16 v124, v125
	v_add_u32_e32 v124, 0x220, v124
	v_fmac_f32_e32 v123, 0x3d800000, v221
	v_add_u32_e32 v126, 0xfffffef0, v124
	v_sub_f32_e32 v128, v122, v123
	v_mul_f32_e32 v128, 0x3fb8aa3b, v128
	v_exp_f32_e32 v128, v128
	v_lshlrev_b32_e32 v127, 16, v137
	v_mul_f32_e32 v127, v128, v127
	v_cvt_pk_bf16_f32 v127, v127, s0
	ds_write_b16 v126, v127
	v_fmac_f32_e32 v123, 0x3d800000, v222
	v_sub_f32_e32 v126, v122, v123
	v_mul_f32_e32 v126, 0x3fb8aa3b, v126
	v_exp_f32_e32 v126, v126
	v_lshlrev_b32_e32 v125, 16, v138
	v_mul_f32_e32 v125, v126, v125
	v_cvt_pk_bf16_f32 v125, v125, s0
	s_addk_i32 s0, 0x80
	ds_write_b16 v124, v125
	v_add_u32_e32 v124, 0x220, v124
	v_fmac_f32_e32 v123, 0x3d800000, v223
	v_add_u32_e32 v126, 0xfffffef0, v124
	v_sub_f32_e32 v128, v122, v123
	v_mul_f32_e32 v128, 0x3fb8aa3b, v128
	v_exp_f32_e32 v128, v128
	v_lshlrev_b32_e32 v127, 16, v139
	v_mul_f32_e32 v127, v128, v127
	v_cvt_pk_bf16_f32 v127, v127, s0
	ds_write_b16 v126, v127
	v_fmac_f32_e32 v123, 0x3d800000, v224
	v_sub_f32_e32 v126, v122, v123
	v_mul_f32_e32 v126, 0x3fb8aa3b, v126
	v_exp_f32_e32 v126, v126
	v_lshlrev_b32_e32 v125, 16, v140
	v_mul_f32_e32 v125, v126, v125
	v_cvt_pk_bf16_f32 v125, v125, s0
	s_addk_i32 s0, 0x80
	ds_write_b16 v124, v125
	v_add_u32_e32 v124, 0x220, v124
	v_fmac_f32_e32 v123, 0x3d800000, v225
	v_add_u32_e32 v126, 0xfffffef0, v124
	v_sub_f32_e32 v128, v122, v123
	v_mul_f32_e32 v128, 0x3fb8aa3b, v128
	v_exp_f32_e32 v128, v128
	v_lshlrev_b32_e32 v127, 16, v141
	v_mul_f32_e32 v127, v128, v127
	v_cvt_pk_bf16_f32 v127, v127, s0
	ds_write_b16 v126, v127
	v_fmac_f32_e32 v123, 0x3d800000, v226
	v_sub_f32_e32 v126, v122, v123
	v_mul_f32_e32 v126, 0x3fb8aa3b, v126
	v_exp_f32_e32 v126, v126
	v_lshlrev_b32_e32 v125, 16, v142
	v_mul_f32_e32 v125, v126, v125
	v_cvt_pk_bf16_f32 v125, v125, s0
	s_addk_i32 s0, 0x80
	ds_write_b16 v124, v125
	v_add_u32_e32 v124, 0x220, v124
	v_fmac_f32_e32 v123, 0x3d800000, v227
	v_add_u32_e32 v126, 0xfffffef0, v124
	v_sub_f32_e32 v128, v122, v123
	v_mul_f32_e32 v128, 0x3fb8aa3b, v128
	v_exp_f32_e32 v128, v128
	v_lshlrev_b32_e32 v127, 16, v143
	v_mul_f32_e32 v127, v128, v127
	v_cvt_pk_bf16_f32 v127, v127, s0
	ds_write_b16 v126, v127
	v_fmac_f32_e32 v123, 0x3d800000, v228
	v_sub_f32_e32 v126, v122, v123
	v_mul_f32_e32 v126, 0x3fb8aa3b, v126
	v_exp_f32_e32 v126, v126
	v_lshlrev_b32_e32 v125, 16, v144
	v_mul_f32_e32 v125, v126, v125
	v_cvt_pk_bf16_f32 v125, v125, s0
	s_addk_i32 s0, 0x80
	ds_write_b16 v124, v125
	v_add_u32_e32 v124, 0x220, v124
	s_and_saveexec_b64 s[12:13], s[2:3]
	s_cbranch_execz .LBB0_510
	v_mul_f32_e32 v8, 0x3fb8aa3b, v122
	v_exp_f32_e32 v8, v8
	s_lshl_b64 s[0:1], s[14:15], 9
	v_lshl_add_u64 v[50:51], v[80:81], 0, s[0:1]
	global_store_dword v[50:51], v8, off
	s_branch .LBB0_510

; DEVI float bf2f(u16 b) { return __uint_as_float(((unsigned)b) << 16); }
; DEVI u16 f2bf(float f) { return (u16)(cvt_pk(f, 0.f) & 0xffffu); }
; template <int KIND>
; DEVI void mix_out_phase(unsigned char* smem, const MixArgs a) {
;     ...
;             for (int t = sg * 32; t < sg * 32 + 32; ++t) { Bc += gla_la(gl, t, w2r, gb);
;                 QS[t * LP + ch] = f2bf(bf2f(QS[t * LP + ch]) * 0.08838834764831845f * __expf(Bc)); KS[t * LP + ch] = f2bf(bf2f(KS[t * LP + ch]) * __expf(-Bc)); }
.LBB0_701:
	v_add_u32_e32 v234, 0xfffffef0, v68
	ds_read_u16 v73, v234 offset:272
	ds_read_u16 v74, v234 offset:35088
	ds_read_u16 v75, v234 offset:544
	ds_read_u16 v76, v234 offset:35360
	ds_read_u16 v77, v234 offset:816
	ds_read_u16 v78, v234 offset:35632
	ds_read_u16 v79, v234 offset:1088
	ds_read_u16 v80, v234 offset:35904
	ds_read_u16 v81, v234 offset:1360
	ds_read_u16 v82, v234 offset:36176
	ds_read_u16 v83, v234 offset:1632
	ds_read_u16 v84, v234 offset:36448
	s_waitcnt lgkmcnt(11)
	ds_read_u16 v85, v234 offset:1904
	s_waitcnt lgkmcnt(11)
	ds_read_u16 v132, v234 offset:36720
	s_waitcnt lgkmcnt(11)
	ds_read_u16 v133, v234 offset:2176
	s_waitcnt lgkmcnt(11)
	ds_read_u16 v140, v234 offset:36992
	s_waitcnt lgkmcnt(11)
	ds_read_u16 v141, v234 offset:2448
	s_waitcnt lgkmcnt(11)
	ds_read_u16 v142, v234 offset:37264
	s_waitcnt lgkmcnt(11)
	ds_read_u16 v143, v234 offset:2720
	s_waitcnt lgkmcnt(11)
	ds_read_u16 v144, v234 offset:37536
	s_waitcnt lgkmcnt(11)
	ds_read_u16 v145, v234 offset:2992
	s_waitcnt lgkmcnt(11)
	ds_read_u16 v162, v234 offset:37808
	s_waitcnt lgkmcnt(11)
	ds_read_u16 v163, v234 offset:3264
	s_waitcnt lgkmcnt(11)
	ds_read_u16 v164, v234 offset:38080
	s_waitcnt lgkmcnt(11)
	ds_read_u16 v165, v234 offset:3536
	s_waitcnt lgkmcnt(11)
	ds_read_u16 v198, v234 offset:38352
	s_waitcnt lgkmcnt(11)
	ds_read_u16 v199, v234 offset:3808
	s_waitcnt lgkmcnt(11)
	ds_read_u16 v229, v234 offset:38624
	s_waitcnt lgkmcnt(11)
	ds_read_u16 v230, v234 offset:4080
	s_waitcnt lgkmcnt(11)
	ds_read_u16 v231, v234 offset:38896
	s_waitcnt lgkmcnt(11)
	ds_read_u16 v232, v234 offset:4352
	s_waitcnt lgkmcnt(11)
	ds_read_u16 v233, v234 offset:39168
	s_waitcnt lgkmcnt(0)
	v_fmac_f32_e32 v67, 0x3d800000, v86
	v_mul_f32_e32 v71, 0x3fb8aa3b, v67
	v_exp_f32_e32 v71, v71
	v_lshlrev_b32_e32 v70, 16, v73
	v_mul_f32_e32 v70, 0x3db504f3, v70
	v_mul_f32_e32 v70, v70, v71
	v_cvt_pk_bf16_f32 v70, v70, s0
	ds_write_b16 v68, v70
	v_mul_f32_e32 v71, 0xbfb8aa3b, v67
	v_exp_f32_e32 v71, v71
	v_lshlrev_b32_e32 v70, 16, v74
	v_mul_f32_e32 v70, v71, v70
	v_cvt_pk_bf16_f32 v70, v70, s0
	ds_write_b16 v68, v70 offset:34816
	v_fmac_f32_e32 v67, 0x3d800000, v87
	v_mul_f32_e32 v70, 0x3fb8aa3b, v67
	v_exp_f32_e32 v70, v70
	v_lshlrev_b32_e32 v69, 16, v75
	v_mul_f32_e32 v69, 0x3db504f3, v69
	v_mul_f32_e32 v69, v69, v70
	v_cvt_pk_bf16_f32 v69, v69, s0
	ds_write_b16 v68, v69 offset:272
	v_mul_f32_e32 v70, 0xbfb8aa3b, v67
	v_exp_f32_e32 v70, v70
	v_lshlrev_b32_e32 v69, 16, v76
	v_mul_f32_e32 v69, v70, v69
	v_cvt_pk_bf16_f32 v69, v69, s0
	s_addk_i32 s0, 0x80
	ds_write_b16 v68, v69 offset:35088
	v_add_u32_e32 v68, 0x220, v68
	v_fmac_f32_e32 v67, 0x3d800000, v88
	v_mul_f32_e32 v71, 0x3fb8aa3b, v67
	v_exp_f32_e32 v71, v71
	v_lshlrev_b32_e32 v70, 16, v77
	v_mul_f32_e32 v70, 0x3db504f3, v70
	v_mul_f32_e32 v70, v70, v71
	v_cvt_pk_bf16_f32 v70, v70, s0
	ds_write_b16 v68, v70
	v_mul_f32_e32 v71, 0xbfb8aa3b, v67
	v_exp_f32_e32 v71, v71
	v_lshlrev_b32_e32 v70, 16, v78
	v_mul_f32_e32 v70, v71, v70
	v_cvt_pk_bf16_f32 v70, v70, s0
	ds_write_b16 v68, v70 offset:34816
	v_fmac_f32_e32 v67, 0x3d800000, v89
	v_mul_f32_e32 v70, 0x3fb8aa3b, v67
	v_exp_f32_e32 v70, v70
	v_lshlrev_b32_e32 v69, 16, v79
	v_mul_f32_e32 v69, 0x3db504f3, v69
	v_mul_f32_e32 v69, v69, v70
	v_cvt_pk_bf16_f32 v69, v69, s0
	ds_write_b16 v68, v69 offset:272
	v_mul_f32_e32 v70, 0xbfb8aa3b, v67
	v_exp_f32_e32 v70, v70
	v_lshlrev_b32_e32 v69, 16, v80
	v_mul_f32_e32 v69, v70, v69
	v_cvt_pk_bf16_f32 v69, v69, s0
	s_addk_i32 s0, 0x80
	ds_write_b16 v68, v69 offset:35088
	v_add_u32_e32 v68, 0x220, v68
	v_fmac_f32_e32 v67, 0x3d800000, v90
	v_mul_f32_e32 v71, 0x3fb8aa3b, v67
	v_exp_f32_e32 v71, v71
	v_lshlrev_b32_e32 v70, 16, v81
	v_mul_f32_e32 v70, 0x3db504f3, v70
	v_mul_f32_e32 v70, v70, v71
	v_cvt_pk_bf16_f32 v70, v70, s0
	ds_write_b16 v68, v70
	v_mul_f32_e32 v71, 0xbfb8aa3b, v67
	v_exp_f32_e32 v71, v71
	v_lshlrev_b32_e32 v70, 16, v82
	v_mul_f32_e32 v70, v71, v70
	v_cvt_pk_bf16_f32 v70, v70, s0
	ds_write_b16 v68, v70 offset:34816
	v_fmac_f32_e32 v67, 0x3d800000, v91
	v_mul_f32_e32 v70, 0x3fb8aa3b, v67
	v_exp_f32_e32 v70, v70
	v_lshlrev_b32_e32 v69, 16, v83
	v_mul_f32_e32 v69, 0x3db504f3, v69
	v_mul_f32_e32 v69, v69, v70
	v_cvt_pk_bf16_f32 v69, v69, s0
	ds_write_b16 v68, v69 offset:272
	v_mul_f32_e32 v70, 0xbfb8aa3b, v67
	v_exp_f32_e32 v70, v70
	v_lshlrev_b32_e32 v69, 16, v84
	v_mul_f32_e32 v69, v70, v69
	v_cvt_pk_bf16_f32 v69, v69, s0
	s_addk_i32 s0, 0x80
	ds_write_b16 v68, v69 offset:35088
	v_add_u32_e32 v68, 0x220, v68
	v_fmac_f32_e32 v67, 0x3d800000, v92
	v_mul_f32_e32 v71, 0x3fb8aa3b, v67
	v_exp_f32_e32 v71, v71
	v_lshlrev_b32_e32 v70, 16, v85
	v_mul_f32_e32 v70, 0x3db504f3, v70
	v_mul_f32_e32 v70, v70, v71
	v_cvt_pk_bf16_f32 v70, v70, s0
	ds_write_b16 v68, v70
	v_mul_f32_e32 v71, 0xbfb8aa3b, v67
	v_exp_f32_e32 v71, v71
	v_lshlrev_b32_e32 v70, 16, v132
	v_mul_f32_e32 v70, v71, v70
	v_cvt_pk_bf16_f32 v70, v70, s0
	ds_write_b16 v68, v70 offset:34816
	v_fmac_f32_e32 v67, 0x3d800000, v93
	v_mul_f32_e32 v70, 0x3fb8aa3b, v67
	v_exp_f32_e32 v70, v70
	v_lshlrev_b32_e32 v69, 16, v133
	v_mul_f32_e32 v69, 0x3db504f3, v69
	v_mul_f32_e32 v69, v69, v70
	v_cvt_pk_bf16_f32 v69, v69, s0
	ds_write_b16 v68, v69 offset:272
	v_mul_f32_e32 v70, 0xbfb8aa3b, v67
	v_exp_f32_e32 v70, v70
	v_lshlrev_b32_e32 v69, 16, v140
	v_mul_f32_e32 v69, v70, v69
	v_cvt_pk_bf16_f32 v69, v69, s0
	s_addk_i32 s0, 0x80
	ds_write_b16 v68, v69 offset:35088
	v_add_u32_e32 v68, 0x220, v68
	v_fmac_f32_e32 v67, 0x3d800000, v94
	v_mul_f32_e32 v71, 0x3fb8aa3b, v67
	v_exp_f32_e32 v71, v71
	v_lshlrev_b32_e32 v70, 16, v141
	v_mul_f32_e32 v70, 0x3db504f3, v70
	v_mul_f32_e32 v70, v70, v71
; DEVI float bf2f(u16 b) { return __uint_as_float(((unsigned)b) << 16); }
; DEVI u16 f2bf(float f) { return (u16)(cvt_pk(f, 0.f) & 0xffffu); }
; template <int KIND>
; DEVI void mix_out_phase(unsigned char* smem, const MixArgs a) {
;     ...
;             for (int t = sg * 32; t < sg * 32 + 32; ++t) { Bc += gla_la(gl, t, w2r, gb);
;                 QS[t * LP + ch] = f2bf(bf2f(QS[t * LP + ch]) * 0.08838834764831845f * __expf(Bc)); KS[t * LP + ch] = f2bf(bf2f(KS[t * LP + ch]) * __expf(-Bc)); }
	v_cvt_pk_bf16_f32 v70, v70, s0
	ds_write_b16 v68, v70
	v_mul_f32_e32 v71, 0xbfb8aa3b, v67
	v_exp_f32_e32 v71, v71
	v_lshlrev_b32_e32 v70, 16, v142
	v_mul_f32_e32 v70, v71, v70
	v_cvt_pk_bf16_f32 v70, v70, s0
	ds_write_b16 v68, v70 offset:34816
	v_fmac_f32_e32 v67, 0x3d800000, v95
	v_mul_f32_e32 v70, 0x3fb8aa3b, v67
	v_exp_f32_e32 v70, v70
	v_lshlrev_b32_e32 v69, 16, v143
	v_mul_f32_e32 v69, 0x3db504f3, v69
	v_mul_f32_e32 v69, v69, v70
	v_cvt_pk_bf16_f32 v69, v69, s0
	ds_write_b16 v68, v69 offset:272
	v_mul_f32_e32 v70, 0xbfb8aa3b, v67
	v_exp_f32_e32 v70, v70
	v_lshlrev_b32_e32 v69, 16, v144
	v_mul_f32_e32 v69, v70, v69
	v_cvt_pk_bf16_f32 v69, v69, s0
	s_addk_i32 s0, 0x80
	ds_write_b16 v68, v69 offset:35088
	v_add_u32_e32 v68, 0x220, v68
	v_fmac_f32_e32 v67, 0x3d800000, v96
	v_mul_f32_e32 v71, 0x3fb8aa3b, v67
	v_exp_f32_e32 v71, v71
	v_lshlrev_b32_e32 v70, 16, v145
	v_mul_f32_e32 v70, 0x3db504f3, v70
	v_mul_f32_e32 v70, v70, v71
	v_cvt_pk_bf16_f32 v70, v70, s0
	ds_write_b16 v68, v70
	v_mul_f32_e32 v71, 0xbfb8aa3b, v67
	v_exp_f32_e32 v71, v71
	v_lshlrev_b32_e32 v70, 16, v162
	v_mul_f32_e32 v70, v71, v70
	v_cvt_pk_bf16_f32 v70, v70, s0
	ds_write_b16 v68, v70 offset:34816
	v_fmac_f32_e32 v67, 0x3d800000, v97
	v_mul_f32_e32 v70, 0x3fb8aa3b, v67
	v_exp_f32_e32 v70, v70
	v_lshlrev_b32_e32 v69, 16, v163
	v_mul_f32_e32 v69, 0x3db504f3, v69
	v_mul_f32_e32 v69, v69, v70
	v_cvt_pk_bf16_f32 v69, v69, s0
	ds_write_b16 v68, v69 offset:272
	v_mul_f32_e32 v70, 0xbfb8aa3b, v67
	v_exp_f32_e32 v70, v70
	v_lshlrev_b32_e32 v69, 16, v164
	v_mul_f32_e32 v69, v70, v69
	v_cvt_pk_bf16_f32 v69, v69, s0
	s_addk_i32 s0, 0x80
	ds_write_b16 v68, v69 offset:35088
	v_add_u32_e32 v68, 0x220, v68
	v_fmac_f32_e32 v67, 0x3d800000, v98
	v_mul_f32_e32 v71, 0x3fb8aa3b, v67
	v_exp_f32_e32 v71, v71
	v_lshlrev_b32_e32 v70, 16, v165
	v_mul_f32_e32 v70, 0x3db504f3, v70
	v_mul_f32_e32 v70, v70, v71
	v_cvt_pk_bf16_f32 v70, v70, s0
	ds_write_b16 v68, v70
	v_mul_f32_e32 v71, 0xbfb8aa3b, v67
	v_exp_f32_e32 v71, v71
	v_lshlrev_b32_e32 v70, 16, v198
	v_mul_f32_e32 v70, v71, v70
	v_cvt_pk_bf16_f32 v70, v70, s0
	ds_write_b16 v68, v70 offset:34816
	v_fmac_f32_e32 v67, 0x3d800000, v99
	v_mul_f32_e32 v70, 0x3fb8aa3b, v67
	v_exp_f32_e32 v70, v70
	v_lshlrev_b32_e32 v69, 16, v199
	v_mul_f32_e32 v69, 0x3db504f3, v69
	v_mul_f32_e32 v69, v69, v70
	v_cvt_pk_bf16_f32 v69, v69, s0
	ds_write_b16 v68, v69 offset:272
	v_mul_f32_e32 v70, 0xbfb8aa3b, v67
	v_exp_f32_e32 v70, v70
	v_lshlrev_b32_e32 v69, 16, v229
	v_mul_f32_e32 v69, v70, v69
	v_cvt_pk_bf16_f32 v69, v69, s0
	s_addk_i32 s0, 0x80
	ds_write_b16 v68, v69 offset:35088
	v_add_u32_e32 v68, 0x220, v68
	v_fmac_f32_e32 v67, 0x3d800000, v116
	v_mul_f32_e32 v71, 0x3fb8aa3b, v67
	v_exp_f32_e32 v71, v71
	v_lshlrev_b32_e32 v70, 16, v230
	v_mul_f32_e32 v70, 0x3db504f3, v70
	v_mul_f32_e32 v70, v70, v71
	v_cvt_pk_bf16_f32 v70, v70, s0
	ds_write_b16 v68, v70
	v_mul_f32_e32 v71, 0xbfb8aa3b, v67
	v_exp_f32_e32 v71, v71
	v_lshlrev_b32_e32 v70, 16, v231
	v_mul_f32_e32 v70, v71, v70
	v_cvt_pk_bf16_f32 v70, v70, s0
	ds_write_b16 v68, v70 offset:34816
	v_fmac_f32_e32 v67, 0x3d800000, v117
	v_mul_f32_e32 v70, 0x3fb8aa3b, v67
	v_exp_f32_e32 v70, v70
	v_lshlrev_b32_e32 v69, 16, v232
	v_mul_f32_e32 v69, 0x3db504f3, v69
	v_mul_f32_e32 v69, v69, v70
	v_cvt_pk_bf16_f32 v69, v69, s0
	ds_write_b16 v68, v69 offset:272
	v_mul_f32_e32 v70, 0xbfb8aa3b, v67
	v_exp_f32_e32 v70, v70
	v_lshlrev_b32_e32 v69, 16, v233
	v_mul_f32_e32 v69, v70, v69
	v_cvt_pk_bf16_f32 v69, v69, s0
	s_addk_i32 s0, 0x80
	ds_write_b16 v68, v69 offset:35088
	v_add_u32_e32 v68, 0x220, v68
	v_add_u32_e32 v234, 0xfffffef0, v68
	ds_read_u16 v73, v234 offset:272
	ds_read_u16 v74, v234 offset:35088
	ds_read_u16 v75, v234 offset:544
	ds_read_u16 v76, v234 offset:35360
	ds_read_u16 v77, v234 offset:816
	ds_read_u16 v78, v234 offset:35632
	ds_read_u16 v79, v234 offset:1088
	ds_read_u16 v80, v234 offset:35904
	ds_read_u16 v81, v234 offset:1360
	ds_read_u16 v82, v234 offset:36176
	ds_read_u16 v83, v234 offset:1632
	ds_read_u16 v84, v234 offset:36448
	s_waitcnt lgkmcnt(11)
	ds_read_u16 v85, v234 offset:1904
	s_waitcnt lgkmcnt(11)
	ds_read_u16 v132, v234 offset:36720
	s_waitcnt lgkmcnt(11)
	ds_read_u16 v133, v234 offset:2176
	s_waitcnt lgkmcnt(11)
	ds_read_u16 v140, v234 offset:36992
	s_waitcnt lgkmcnt(11)
	ds_read_u16 v141, v234 offset:2448
	s_waitcnt lgkmcnt(11)
	ds_read_u16 v142, v234 offset:37264
	s_waitcnt lgkmcnt(11)
	ds_read_u16 v143, v234 offset:2720
	s_waitcnt lgkmcnt(11)
	ds_read_u16 v144, v234 offset:37536
	s_waitcnt lgkmcnt(11)
	ds_read_u16 v145, v234 offset:2992
	s_waitcnt lgkmcnt(11)
	ds_read_u16 v162, v234 offset:37808
	s_waitcnt lgkmcnt(11)
	ds_read_u16 v163, v234 offset:3264
	s_waitcnt lgkmcnt(11)
	ds_read_u16 v164, v234 offset:38080
	s_waitcnt lgkmcnt(11)
	ds_read_u16 v165, v234 offset:3536
	s_waitcnt lgkmcnt(11)
	ds_read_u16 v198, v234 offset:38352
	s_waitcnt lgkmcnt(11)
	ds_read_u16 v199, v234 offset:3808
	s_waitcnt lgkmcnt(11)
	ds_read_u16 v229, v234 offset:38624
	s_waitcnt lgkmcnt(11)
	ds_read_u16 v230, v234 offset:4080
	s_waitcnt lgkmcnt(11)
	ds_read_u16 v231, v234 offset:38896
	s_waitcnt lgkmcnt(11)
	ds_read_u16 v232, v234 offset:4352
	s_waitcnt lgkmcnt(11)
	ds_read_u16 v233, v234 offset:39168
	s_waitcnt lgkmcnt(0)
; DEVI float bf2f(u16 b) { return __uint_as_float(((unsigned)b) << 16); }
; DEVI u16 f2bf(float f) { return (u16)(cvt_pk(f, 0.f) & 0xffffu); }
; template <int KIND>
; DEVI void mix_out_phase(unsigned char* smem, const MixArgs a) {
;     ...
;             float Bc = 0.f;
; #pragma unroll
;             for (int s2 = 0; s2 < 4; ++s2) { const float v = seg[s2 * 128 + ch]; if (s2 < sg) Bc += v; }
;             for (int t = sg * 32; t < sg * 32 + 32; ++t) { Bc += gla_la(gl, t, w2r, gb);
;                 QS[t * LP + ch] = f2bf(bf2f(QS[t * LP + ch]) * 0.08838834764831845f * __expf(Bc)); KS[t * LP + ch] = f2bf(bf2f(KS[t * LP + ch]) * __expf(-Bc)); }
;         }
	v_fmac_f32_e32 v67, 0x3d800000, v118
	v_mul_f32_e32 v71, 0x3fb8aa3b, v67
	v_exp_f32_e32 v71, v71
	v_lshlrev_b32_e32 v70, 16, v73
	v_mul_f32_e32 v70, 0x3db504f3, v70
	v_mul_f32_e32 v70, v70, v71
	v_cvt_pk_bf16_f32 v70, v70, s0
	ds_write_b16 v68, v70
	v_mul_f32_e32 v71, 0xbfb8aa3b, v67
	v_exp_f32_e32 v71, v71
	v_lshlrev_b32_e32 v70, 16, v74
	v_mul_f32_e32 v70, v71, v70
	v_cvt_pk_bf16_f32 v70, v70, s0
	ds_write_b16 v68, v70 offset:34816
	v_fmac_f32_e32 v67, 0x3d800000, v119
	v_mul_f32_e32 v70, 0x3fb8aa3b, v67
	v_exp_f32_e32 v70, v70
	v_lshlrev_b32_e32 v69, 16, v75
	v_mul_f32_e32 v69, 0x3db504f3, v69
	v_mul_f32_e32 v69, v69, v70
	v_cvt_pk_bf16_f32 v69, v69, s0
	ds_write_b16 v68, v69 offset:272
	v_mul_f32_e32 v70, 0xbfb8aa3b, v67
	v_exp_f32_e32 v70, v70
	v_lshlrev_b32_e32 v69, 16, v76
	v_mul_f32_e32 v69, v70, v69
	v_cvt_pk_bf16_f32 v69, v69, s0
	s_addk_i32 s0, 0x80
	ds_write_b16 v68, v69 offset:35088
	v_add_u32_e32 v68, 0x220, v68
	v_fmac_f32_e32 v67, 0x3d800000, v120
	v_mul_f32_e32 v71, 0x3fb8aa3b, v67
	v_exp_f32_e32 v71, v71
	v_lshlrev_b32_e32 v70, 16, v77
	v_mul_f32_e32 v70, 0x3db504f3, v70
	v_mul_f32_e32 v70, v70, v71
	v_cvt_pk_bf16_f32 v70, v70, s0
	ds_write_b16 v68, v70
	v_mul_f32_e32 v71, 0xbfb8aa3b, v67
	v_exp_f32_e32 v71, v71
	v_lshlrev_b32_e32 v70, 16, v78
	v_mul_f32_e32 v70, v71, v70
	v_cvt_pk_bf16_f32 v70, v70, s0
	ds_write_b16 v68, v70 offset:34816
	v_fmac_f32_e32 v67, 0x3d800000, v121
	v_mul_f32_e32 v70, 0x3fb8aa3b, v67
	v_exp_f32_e32 v70, v70
	v_lshlrev_b32_e32 v69, 16, v79
	v_mul_f32_e32 v69, 0x3db504f3, v69
	v_mul_f32_e32 v69, v69, v70
	v_cvt_pk_bf16_f32 v69, v69, s0
	ds_write_b16 v68, v69 offset:272
	v_mul_f32_e32 v70, 0xbfb8aa3b, v67
	v_exp_f32_e32 v70, v70
	v_lshlrev_b32_e32 v69, 16, v80
	v_mul_f32_e32 v69, v70, v69
	v_cvt_pk_bf16_f32 v69, v69, s0
	s_addk_i32 s0, 0x80
	ds_write_b16 v68, v69 offset:35088
	v_add_u32_e32 v68, 0x220, v68
	v_fmac_f32_e32 v67, 0x3d800000, v122
	v_mul_f32_e32 v71, 0x3fb8aa3b, v67
	v_exp_f32_e32 v71, v71
	v_lshlrev_b32_e32 v70, 16, v81
	v_mul_f32_e32 v70, 0x3db504f3, v70
	v_mul_f32_e32 v70, v70, v71
	v_cvt_pk_bf16_f32 v70, v70, s0
	ds_write_b16 v68, v70
	v_mul_f32_e32 v71, 0xbfb8aa3b, v67
	v_exp_f32_e32 v71, v71
	v_lshlrev_b32_e32 v70, 16, v82
	v_mul_f32_e32 v70, v71, v70
	v_cvt_pk_bf16_f32 v70, v70, s0
	ds_write_b16 v68, v70 offset:34816
	v_fmac_f32_e32 v67, 0x3d800000, v123
	v_mul_f32_e32 v70, 0x3fb8aa3b, v67
	v_exp_f32_e32 v70, v70
	v_lshlrev_b32_e32 v69, 16, v83
	v_mul_f32_e32 v69, 0x3db504f3, v69
	v_mul_f32_e32 v69, v69, v70
	v_cvt_pk_bf16_f32 v69, v69, s0
	ds_write_b16 v68, v69 offset:272
	v_mul_f32_e32 v70, 0xbfb8aa3b, v67
	v_exp_f32_e32 v70, v70
	v_lshlrev_b32_e32 v69, 16, v84
	v_mul_f32_e32 v69, v70, v69
	v_cvt_pk_bf16_f32 v69, v69, s0
	s_addk_i32 s0, 0x80
	ds_write_b16 v68, v69 offset:35088
	v_add_u32_e32 v68, 0x220, v68
	v_fmac_f32_e32 v67, 0x3d800000, v124
	v_mul_f32_e32 v71, 0x3fb8aa3b, v67
	v_exp_f32_e32 v71, v71
	v_lshlrev_b32_e32 v70, 16, v85
	v_mul_f32_e32 v70, 0x3db504f3, v70
	v_mul_f32_e32 v70, v70, v71
	v_cvt_pk_bf16_f32 v70, v70, s0
	ds_write_b16 v68, v70
	v_mul_f32_e32 v71, 0xbfb8aa3b, v67
	v_exp_f32_e32 v71, v71
	v_lshlrev_b32_e32 v70, 16, v132
	v_mul_f32_e32 v70, v71, v70
	v_cvt_pk_bf16_f32 v70, v70, s0
	ds_write_b16 v68, v70 offset:34816
	v_fmac_f32_e32 v67, 0x3d800000, v125
	v_mul_f32_e32 v70, 0x3fb8aa3b, v67
	v_exp_f32_e32 v70, v70
	v_lshlrev_b32_e32 v69, 16, v133
	v_mul_f32_e32 v69, 0x3db504f3, v69
	v_mul_f32_e32 v69, v69, v70
	v_cvt_pk_bf16_f32 v69, v69, s0
	ds_write_b16 v68, v69 offset:272
	v_mul_f32_e32 v70, 0xbfb8aa3b, v67
	v_exp_f32_e32 v70, v70
	v_lshlrev_b32_e32 v69, 16, v140
	v_mul_f32_e32 v69, v70, v69
	v_cvt_pk_bf16_f32 v69, v69, s0
	s_addk_i32 s0, 0x80
	ds_write_b16 v68, v69 offset:35088
	v_add_u32_e32 v68, 0x220, v68
	v_fmac_f32_e32 v67, 0x3d800000, v126
	v_mul_f32_e32 v71, 0x3fb8aa3b, v67
	v_exp_f32_e32 v71, v71
	v_lshlrev_b32_e32 v70, 16, v141
	v_mul_f32_e32 v70, 0x3db504f3, v70
	v_mul_f32_e32 v70, v70, v71
; DEVI float bf2f(u16 b) { return __uint_as_float(((unsigned)b) << 16); }
; DEVI u16 f2bf(float f) { return (u16)(cvt_pk(f, 0.f) & 0xffffu); }
; DEVI void lds_barrier() { asm volatile("s_waitcnt lgkmcnt(0)\n\ts_barrier" ::: "memory"); }
; template <int KIND>
; DEVI void mix_out_phase(unsigned char* smem, const MixArgs a) {
;     ...
;             for (int t = sg * 32; t < sg * 32 + 32; ++t) { Bc += gla_la(gl, t, w2r, gb);
;                 QS[t * LP + ch] = f2bf(bf2f(QS[t * LP + ch]) * 0.08838834764831845f * __expf(Bc)); KS[t * LP + ch] = f2bf(bf2f(KS[t * LP + ch]) * __expf(-Bc)); }
;         }
;         lds_barrier();
;         bf16x8 qa[4];
; #pragma unroll
;         for (int ks = 0; ks < 4; ++ks) qa[ks] = *(const bf16x8*)(QS + trow * LP + ks * 32 + fq * 8);
;         float rowsum = 0.f; const float bt = (KIND == 0) ? fB[trow] : 0.f;
;         const int nmax = wid | 1;
;         for (int n = 0; n <= nmax; ++n) { f32x4 s = (f32x4){0.f, 0.f, 0.f, 0.f};
	v_cvt_pk_bf16_f32 v70, v70, s0
	ds_write_b16 v68, v70
	v_mul_f32_e32 v71, 0xbfb8aa3b, v67
	v_exp_f32_e32 v71, v71
	v_lshlrev_b32_e32 v70, 16, v142
	v_mul_f32_e32 v70, v71, v70
	v_cvt_pk_bf16_f32 v70, v70, s0
	ds_write_b16 v68, v70 offset:34816
	v_fmac_f32_e32 v67, 0x3d800000, v127
	v_mul_f32_e32 v70, 0x3fb8aa3b, v67
	v_exp_f32_e32 v70, v70
	v_lshlrev_b32_e32 v69, 16, v143
	v_mul_f32_e32 v69, 0x3db504f3, v69
	v_mul_f32_e32 v69, v69, v70
	v_cvt_pk_bf16_f32 v69, v69, s0
	ds_write_b16 v68, v69 offset:272
	v_mul_f32_e32 v70, 0xbfb8aa3b, v67
	v_exp_f32_e32 v70, v70
	v_lshlrev_b32_e32 v69, 16, v144
	v_mul_f32_e32 v69, v70, v69
	v_cvt_pk_bf16_f32 v69, v69, s0
	s_addk_i32 s0, 0x80
	ds_write_b16 v68, v69 offset:35088
	v_add_u32_e32 v68, 0x220, v68
	v_fmac_f32_e32 v67, 0x3d800000, v128
	v_mul_f32_e32 v71, 0x3fb8aa3b, v67
	v_exp_f32_e32 v71, v71
	v_lshlrev_b32_e32 v70, 16, v145
	v_mul_f32_e32 v70, 0x3db504f3, v70
	v_mul_f32_e32 v70, v70, v71
	v_cvt_pk_bf16_f32 v70, v70, s0
	ds_write_b16 v68, v70
	v_mul_f32_e32 v71, 0xbfb8aa3b, v67
	v_exp_f32_e32 v71, v71
	v_lshlrev_b32_e32 v70, 16, v162
	v_mul_f32_e32 v70, v71, v70
	v_cvt_pk_bf16_f32 v70, v70, s0
	ds_write_b16 v68, v70 offset:34816
	v_fmac_f32_e32 v67, 0x3d800000, v129
	v_mul_f32_e32 v70, 0x3fb8aa3b, v67
	v_exp_f32_e32 v70, v70
	v_lshlrev_b32_e32 v69, 16, v163
	v_mul_f32_e32 v69, 0x3db504f3, v69
	v_mul_f32_e32 v69, v69, v70
	v_cvt_pk_bf16_f32 v69, v69, s0
	ds_write_b16 v68, v69 offset:272
	v_mul_f32_e32 v70, 0xbfb8aa3b, v67
	v_exp_f32_e32 v70, v70
	v_lshlrev_b32_e32 v69, 16, v164
	v_mul_f32_e32 v69, v70, v69
	v_cvt_pk_bf16_f32 v69, v69, s0
	s_addk_i32 s0, 0x80
	ds_write_b16 v68, v69 offset:35088
	v_add_u32_e32 v68, 0x220, v68
	v_fmac_f32_e32 v67, 0x3d800000, v136
	v_mul_f32_e32 v71, 0x3fb8aa3b, v67
	v_exp_f32_e32 v71, v71
	v_lshlrev_b32_e32 v70, 16, v165
	v_mul_f32_e32 v70, 0x3db504f3, v70
	v_mul_f32_e32 v70, v70, v71
	v_cvt_pk_bf16_f32 v70, v70, s0
	ds_write_b16 v68, v70
	v_mul_f32_e32 v71, 0xbfb8aa3b, v67
	v_exp_f32_e32 v71, v71
	v_lshlrev_b32_e32 v70, 16, v198
	v_mul_f32_e32 v70, v71, v70
	v_cvt_pk_bf16_f32 v70, v70, s0
	ds_write_b16 v68, v70 offset:34816
	v_fmac_f32_e32 v67, 0x3d800000, v137
	v_mul_f32_e32 v70, 0x3fb8aa3b, v67
	v_exp_f32_e32 v70, v70
	v_lshlrev_b32_e32 v69, 16, v199
	v_mul_f32_e32 v69, 0x3db504f3, v69
	v_mul_f32_e32 v69, v69, v70
	v_cvt_pk_bf16_f32 v69, v69, s0
	ds_write_b16 v68, v69 offset:272
	v_mul_f32_e32 v70, 0xbfb8aa3b, v67
	v_exp_f32_e32 v70, v70
	v_lshlrev_b32_e32 v69, 16, v229
	v_mul_f32_e32 v69, v70, v69
	v_cvt_pk_bf16_f32 v69, v69, s0
	s_addk_i32 s0, 0x80
	ds_write_b16 v68, v69 offset:35088
	v_add_u32_e32 v68, 0x220, v68
	v_fmac_f32_e32 v67, 0x3d800000, v138
	v_mul_f32_e32 v71, 0x3fb8aa3b, v67
	v_exp_f32_e32 v71, v71
	v_lshlrev_b32_e32 v70, 16, v230
	v_mul_f32_e32 v70, 0x3db504f3, v70
	v_mul_f32_e32 v70, v70, v71
	v_cvt_pk_bf16_f32 v70, v70, s0
	ds_write_b16 v68, v70
	v_mul_f32_e32 v71, 0xbfb8aa3b, v67
	v_exp_f32_e32 v71, v71
	v_lshlrev_b32_e32 v70, 16, v231
	v_mul_f32_e32 v70, v71, v70
	v_cvt_pk_bf16_f32 v70, v70, s0
	ds_write_b16 v68, v70 offset:34816
	v_fmac_f32_e32 v67, 0x3d800000, v139
	v_mul_f32_e32 v70, 0x3fb8aa3b, v67
	v_exp_f32_e32 v70, v70
	v_lshlrev_b32_e32 v69, 16, v232
	v_mul_f32_e32 v69, 0x3db504f3, v69
	v_mul_f32_e32 v69, v69, v70
	v_cvt_pk_bf16_f32 v69, v69, s0
	ds_write_b16 v68, v69 offset:272
	v_mul_f32_e32 v70, 0xbfb8aa3b, v67
	v_exp_f32_e32 v70, v70
	v_lshlrev_b32_e32 v69, 16, v233
	v_mul_f32_e32 v69, v70, v69
	v_cvt_pk_bf16_f32 v69, v69, s0
	s_addk_i32 s0, 0x80
	ds_write_b16 v68, v69 offset:35088
	v_add_u32_e32 v68, 0x220, v68
	s_waitcnt lgkmcnt(0)
	s_barrier
	ds_read_b128 v[94:97], v225 offset:16384
	ds_read_b128 v[90:93], v225 offset:16448
	ds_read_b128 v[86:89], v225 offset:16512
	ds_read_b128 v[82:85], v225 offset:16576
	s_and_saveexec_b64 s[14:15], s[2:3]
	s_cbranch_execz .LBB0_707
	s_mov_b32 s0, 0
	s_mov_b64 s[82:83], 0
	v_mov_b32_e32 v34, v218
	v_mov_b32_e32 v35, v216
	v_mov_b32_e32 v36, v206
	s_branch .LBB0_705
